# tail-fill conversion, 8 sites with capped per-site loads (GEMM tails <= ~10k items, M1/M3/LRU last rounds ~4-5k), P0 keeps gate-up layer 0 + AB input projection only
# speedup vs baseline: 1.0066x; 1.0028x over previous
.LBB0_302:
	s_cmpk_lg_i32 s33, 0x100
	s_cbranch_scc1 .Lmy_skip_p2
	s_cmp_lt_u32 s76, 108
	s_cbranch_scc1 .Lmy_skip_p2
	s_waitcnt vmcnt(0) lgkmcnt(0)
	s_barrier
	v_writelane_b32 v255, s0, 0
	v_writelane_b32 v255, s1, 1
	v_writelane_b32 v255, s2, 2
	v_writelane_b32 v255, s3, 3
	v_writelane_b32 v255, s4, 4
	v_writelane_b32 v255, s5, 5
	v_writelane_b32 v255, s6, 6
	v_writelane_b32 v255, s7, 7
	v_writelane_b32 v255, s8, 8
	v_writelane_b32 v255, s9, 9
	v_writelane_b32 v255, s10, 10
	v_writelane_b32 v255, s11, 11
	v_writelane_b32 v255, s12, 12
	v_writelane_b32 v255, s13, 13
	v_writelane_b32 v255, s14, 14
	v_writelane_b32 v255, s15, 15
	v_writelane_b32 v255, s16, 16
	v_writelane_b32 v255, s17, 17
	v_writelane_b32 v255, s18, 18
	v_writelane_b32 v255, s19, 19
	v_writelane_b32 v255, s20, 20
	v_writelane_b32 v255, s21, 21
	v_writelane_b32 v255, s22, 22
	v_writelane_b32 v255, s23, 23
	v_writelane_b32 v255, s26, 24
	v_writelane_b32 v255, s27, 25
	v_writelane_b32 v255, s34, 26
	v_writelane_b32 v255, s35, 27
	v_writelane_b32 v255, s36, 28
	v_writelane_b32 v255, s37, 29
	v_writelane_b32 v255, s38, 30
	v_writelane_b32 v255, s39, 31
	v_writelane_b32 v255, s40, 32
	v_writelane_b32 v255, s41, 33
	v_writelane_b32 v255, s42, 34
	v_writelane_b32 v255, s43, 35
	v_writelane_b32 v255, s44, 36
	v_writelane_b32 v255, s45, 37
	v_writelane_b32 v255, s46, 38
	v_writelane_b32 v255, s47, 39
	v_writelane_b32 v255, s48, 40
	v_writelane_b32 v255, s49, 41
	v_writelane_b32 v255, s50, 42
	v_writelane_b32 v255, s51, 43
	v_writelane_b32 v255, s52, 44
	v_writelane_b32 v255, s53, 45
	v_writelane_b32 v255, s54, 46
	v_writelane_b32 v255, s55, 47
	v_writelane_b32 v255, s56, 48
	v_writelane_b32 v255, s57, 49
	v_writelane_b32 v255, s58, 50
	v_writelane_b32 v255, s59, 51
	v_writelane_b32 v255, s60, 52
	v_writelane_b32 v255, s61, 53
	v_writelane_b32 v255, s62, 54
	v_writelane_b32 v255, s63, 55
	v_writelane_b32 v255, s64, 56
	v_writelane_b32 v255, s65, 57
	v_writelane_b32 v255, s66, 58
	v_writelane_b32 v255, s67, 59
	v_writelane_b32 v255, s68, 60
	v_writelane_b32 v255, s69, 61
	v_writelane_b32 v255, s70, 62
	v_writelane_b32 v255, s71, 63
	v_writelane_b32 v254, s76, 0
	v_writelane_b32 v254, s77, 1
	v_writelane_b32 v254, s80, 2
	v_writelane_b32 v254, s81, 3
	v_writelane_b32 v254, s82, 4
	v_writelane_b32 v254, s83, 5
	v_writelane_b32 v254, s84, 6
	v_writelane_b32 v254, s85, 7
	v_writelane_b32 v254, s86, 8
	v_writelane_b32 v254, s87, 9
	v_writelane_b32 v254, s88, 10
	v_writelane_b32 v254, s89, 11
	v_writelane_b32 v254, s90, 12
	v_writelane_b32 v254, s91, 13
	v_writelane_b32 v254, s92, 14
	v_writelane_b32 v254, s93, 15
	v_writelane_b32 v254, s94, 16
	v_writelane_b32 v254, s95, 17
	v_writelane_b32 v254, s96, 18
	v_writelane_b32 v254, s97, 19
	s_sub_i32 s98, s76, 108
	s_lshl_b32 s98, s98, 3
	s_add_i32 s98, s98, s25
	s_add_i32 s98, s98, 0x4400
	s_movk_i32 s99, 0x4a0
	s_mov_b32 s100, 0x6b10
	s_mov_b32 s101, 1
	s_add_u32 s0, s78, 0xfffffef0
	s_addc_u32 s1, s79, -1
	s_load_dwordx8 s[36:43], s[0:1], 0x40
	s_waitcnt lgkmcnt(0)
	s_branch .Lmy_cvt_entry

.LBB0_716:
	s_waitcnt vmcnt(0)
	s_barrier
	s_cmpk_lg_i32 s33, 0x100
	s_cbranch_scc1 .Lmy_skip_p5
	s_cmp_lt_u32 s76, 164
	s_cbranch_scc1 .Lmy_skip_p5
	s_waitcnt vmcnt(0) lgkmcnt(0)
	s_barrier
	v_writelane_b32 v255, s0, 0
	v_writelane_b32 v255, s1, 1
	v_writelane_b32 v255, s2, 2
	v_writelane_b32 v255, s3, 3
	v_writelane_b32 v255, s4, 4
	v_writelane_b32 v255, s5, 5
	v_writelane_b32 v255, s6, 6
	v_writelane_b32 v255, s7, 7
	v_writelane_b32 v255, s8, 8
	v_writelane_b32 v255, s9, 9
	v_writelane_b32 v255, s10, 10
	v_writelane_b32 v255, s11, 11
	v_writelane_b32 v255, s12, 12
	v_writelane_b32 v255, s13, 13
	v_writelane_b32 v255, s14, 14
	v_writelane_b32 v255, s15, 15
	v_writelane_b32 v255, s16, 16
	v_writelane_b32 v255, s17, 17
	v_writelane_b32 v255, s18, 18
	v_writelane_b32 v255, s19, 19
	v_writelane_b32 v255, s20, 20
	v_writelane_b32 v255, s21, 21
	v_writelane_b32 v255, s22, 22
	v_writelane_b32 v255, s23, 23
	v_writelane_b32 v255, s26, 24
	v_writelane_b32 v255, s27, 25
	v_writelane_b32 v255, s34, 26
	v_writelane_b32 v255, s35, 27
	v_writelane_b32 v255, s36, 28
	v_writelane_b32 v255, s37, 29
	v_writelane_b32 v255, s38, 30
	v_writelane_b32 v255, s39, 31
	v_writelane_b32 v255, s40, 32
	v_writelane_b32 v255, s41, 33
	v_writelane_b32 v255, s42, 34
	v_writelane_b32 v255, s43, 35
	v_writelane_b32 v255, s44, 36
	v_writelane_b32 v255, s45, 37
	v_writelane_b32 v255, s46, 38
	v_writelane_b32 v255, s47, 39
	v_writelane_b32 v255, s48, 40
	v_writelane_b32 v255, s49, 41
	v_writelane_b32 v255, s50, 42
	v_writelane_b32 v255, s51, 43
	v_writelane_b32 v255, s52, 44
	v_writelane_b32 v255, s53, 45
	v_writelane_b32 v255, s54, 46
	v_writelane_b32 v255, s55, 47
	v_writelane_b32 v255, s56, 48
	v_writelane_b32 v255, s57, 49
	v_writelane_b32 v255, s58, 50
	v_writelane_b32 v255, s59, 51
	v_writelane_b32 v255, s60, 52
	v_writelane_b32 v255, s61, 53
	v_writelane_b32 v255, s62, 54
	v_writelane_b32 v255, s63, 55
	v_writelane_b32 v255, s64, 56
	v_writelane_b32 v255, s65, 57
	v_writelane_b32 v255, s66, 58
	v_writelane_b32 v255, s67, 59
	v_writelane_b32 v255, s68, 60
	v_writelane_b32 v255, s69, 61
	v_writelane_b32 v255, s70, 62
	v_writelane_b32 v255, s71, 63
	v_writelane_b32 v254, s76, 0
	v_writelane_b32 v254, s77, 1
	v_writelane_b32 v254, s80, 2
	v_writelane_b32 v254, s81, 3
	v_writelane_b32 v254, s82, 4
	v_writelane_b32 v254, s83, 5
	v_writelane_b32 v254, s84, 6
	v_writelane_b32 v254, s85, 7
	v_writelane_b32 v254, s86, 8
	v_writelane_b32 v254, s87, 9
	v_writelane_b32 v254, s88, 10
	v_writelane_b32 v254, s89, 11
	v_writelane_b32 v254, s90, 12
	v_writelane_b32 v254, s91, 13
	v_writelane_b32 v254, s92, 14
	v_writelane_b32 v254, s93, 15
	v_writelane_b32 v254, s94, 16
	v_writelane_b32 v254, s95, 17
	v_writelane_b32 v254, s96, 18
	v_writelane_b32 v254, s97, 19
	s_sub_i32 s98, s76, 164
	s_lshl_b32 s98, s98, 3
	s_add_i32 s98, s98, s25
	s_add_i32 s98, s98, 0x6b10
	s_movk_i32 s99, 0x2e0
	s_mov_b32 s100, 0x8668
	s_mov_b32 s101, 2
	s_add_u32 s0, s78, 0xfffffef0
	s_addc_u32 s1, s79, -1
	s_load_dwordx8 s[36:43], s[0:1], 0x40
	s_waitcnt lgkmcnt(0)
	s_branch .Lmy_cvt_entry

.LBB0_790:
	s_cmpk_lg_i32 s33, 0x100
	s_cbranch_scc1 .Lmy_skip_m1
	s_cmp_lt_u32 s24, 64
	s_cbranch_scc1 .Lmy_skip_m1
	s_waitcnt vmcnt(0) lgkmcnt(0)
	s_barrier
	v_writelane_b32 v255, s0, 0
	v_writelane_b32 v255, s1, 1
	v_writelane_b32 v255, s2, 2
	v_writelane_b32 v255, s3, 3
	v_writelane_b32 v255, s4, 4
	v_writelane_b32 v255, s5, 5
	v_writelane_b32 v255, s6, 6
	v_writelane_b32 v255, s7, 7
	v_writelane_b32 v255, s8, 8
	v_writelane_b32 v255, s9, 9
	v_writelane_b32 v255, s10, 10
	v_writelane_b32 v255, s11, 11
	v_writelane_b32 v255, s12, 12
	v_writelane_b32 v255, s13, 13
	v_writelane_b32 v255, s14, 14
	v_writelane_b32 v255, s15, 15
	v_writelane_b32 v255, s16, 16
	v_writelane_b32 v255, s17, 17
	v_writelane_b32 v255, s18, 18
	v_writelane_b32 v255, s19, 19
	v_writelane_b32 v255, s20, 20
	v_writelane_b32 v255, s21, 21
	v_writelane_b32 v255, s22, 22
	v_writelane_b32 v255, s23, 23
	v_writelane_b32 v255, s26, 24
	v_writelane_b32 v255, s27, 25
	v_writelane_b32 v255, s34, 26
	v_writelane_b32 v255, s35, 27
	v_writelane_b32 v255, s36, 28
	v_writelane_b32 v255, s37, 29
	v_writelane_b32 v255, s38, 30
	v_writelane_b32 v255, s39, 31
	v_writelane_b32 v255, s40, 32
	v_writelane_b32 v255, s41, 33
	v_writelane_b32 v255, s42, 34
	v_writelane_b32 v255, s43, 35
	v_writelane_b32 v255, s44, 36
	v_writelane_b32 v255, s45, 37
	v_writelane_b32 v255, s46, 38
	v_writelane_b32 v255, s47, 39
	v_writelane_b32 v255, s48, 40
	v_writelane_b32 v255, s49, 41
	v_writelane_b32 v255, s50, 42
	v_writelane_b32 v255, s51, 43
	v_writelane_b32 v255, s52, 44
	v_writelane_b32 v255, s53, 45
	v_writelane_b32 v255, s54, 46
	v_writelane_b32 v255, s55, 47
	v_writelane_b32 v255, s56, 48
	v_writelane_b32 v255, s57, 49
	v_writelane_b32 v255, s58, 50
	v_writelane_b32 v255, s59, 51
	v_writelane_b32 v255, s60, 52
	v_writelane_b32 v255, s61, 53
	v_writelane_b32 v255, s62, 54
	v_writelane_b32 v255, s63, 55
	v_writelane_b32 v255, s64, 56
	v_writelane_b32 v255, s65, 57
	v_writelane_b32 v255, s66, 58
	v_writelane_b32 v255, s67, 59
	v_writelane_b32 v255, s68, 60
	v_writelane_b32 v255, s69, 61
	v_writelane_b32 v255, s70, 62
	v_writelane_b32 v255, s71, 63
	v_writelane_b32 v254, s76, 0
	v_writelane_b32 v254, s77, 1
	v_writelane_b32 v254, s80, 2
	v_writelane_b32 v254, s81, 3
	v_writelane_b32 v254, s82, 4
	v_writelane_b32 v254, s83, 5
	v_writelane_b32 v254, s84, 6
	v_writelane_b32 v254, s85, 7
	v_writelane_b32 v254, s86, 8
	v_writelane_b32 v254, s87, 9
	v_writelane_b32 v254, s88, 10
	v_writelane_b32 v254, s89, 11
	v_writelane_b32 v254, s90, 12
	v_writelane_b32 v254, s91, 13
	v_writelane_b32 v254, s92, 14
	v_writelane_b32 v254, s93, 15
	v_writelane_b32 v254, s94, 16
	v_writelane_b32 v254, s95, 17
	v_writelane_b32 v254, s96, 18
	v_writelane_b32 v254, s97, 19
	s_sub_i32 s98, s24, 64
	s_lshl_b32 s98, s98, 3
	s_add_i32 s98, s98, s25
	s_add_i32 s98, s98, 0x8668
	s_movk_i32 s99, 0x600
	s_mov_b32 s100, 0x9540
	s_mov_b32 s101, 7
	s_add_u32 s0, s78, 0xfffffef0
	s_addc_u32 s1, s79, -1
	s_load_dwordx8 s[36:43], s[0:1], 0x40
	s_waitcnt lgkmcnt(0)
	s_branch .Lmy_cvt_entry

.LBB0_1255:
	s_cmpk_lg_i32 s33, 0x100
	s_cbranch_scc1 .Lmy_skip_m3
	s_cmp_lt_u32 s24, 64
	s_cbranch_scc1 .Lmy_skip_m3
	s_waitcnt vmcnt(0) lgkmcnt(0)
	s_barrier
	v_writelane_b32 v255, s0, 0
	v_writelane_b32 v255, s1, 1
	v_writelane_b32 v255, s2, 2
	v_writelane_b32 v255, s3, 3
	v_writelane_b32 v255, s4, 4
	v_writelane_b32 v255, s5, 5
	v_writelane_b32 v255, s6, 6
	v_writelane_b32 v255, s7, 7
	v_writelane_b32 v255, s8, 8
	v_writelane_b32 v255, s9, 9
	v_writelane_b32 v255, s10, 10
	v_writelane_b32 v255, s11, 11
	v_writelane_b32 v255, s12, 12
	v_writelane_b32 v255, s13, 13
	v_writelane_b32 v255, s14, 14
	v_writelane_b32 v255, s15, 15
	v_writelane_b32 v255, s16, 16
	v_writelane_b32 v255, s17, 17
	v_writelane_b32 v255, s18, 18
	v_writelane_b32 v255, s19, 19
	v_writelane_b32 v255, s20, 20
	v_writelane_b32 v255, s21, 21
	v_writelane_b32 v255, s22, 22
	v_writelane_b32 v255, s23, 23
	v_writelane_b32 v255, s26, 24
	v_writelane_b32 v255, s27, 25
	v_writelane_b32 v255, s34, 26
	v_writelane_b32 v255, s35, 27
	v_writelane_b32 v255, s36, 28
	v_writelane_b32 v255, s37, 29
	v_writelane_b32 v255, s38, 30
	v_writelane_b32 v255, s39, 31
	v_writelane_b32 v255, s40, 32
	v_writelane_b32 v255, s41, 33
	v_writelane_b32 v255, s42, 34
	v_writelane_b32 v255, s43, 35
	v_writelane_b32 v255, s44, 36
	v_writelane_b32 v255, s45, 37
	v_writelane_b32 v255, s46, 38
	v_writelane_b32 v255, s47, 39
	v_writelane_b32 v255, s48, 40
	v_writelane_b32 v255, s49, 41
	v_writelane_b32 v255, s50, 42
	v_writelane_b32 v255, s51, 43
	v_writelane_b32 v255, s52, 44
	v_writelane_b32 v255, s53, 45
	v_writelane_b32 v255, s54, 46
	v_writelane_b32 v255, s55, 47
	v_writelane_b32 v255, s56, 48
	v_writelane_b32 v255, s57, 49
	v_writelane_b32 v255, s58, 50
	v_writelane_b32 v255, s59, 51
	v_writelane_b32 v255, s60, 52
	v_writelane_b32 v255, s61, 53
	v_writelane_b32 v255, s62, 54
	v_writelane_b32 v255, s63, 55
	v_writelane_b32 v255, s64, 56
	v_writelane_b32 v255, s65, 57
	v_writelane_b32 v255, s66, 58
	v_writelane_b32 v255, s67, 59
	v_writelane_b32 v255, s68, 60
	v_writelane_b32 v255, s69, 61
	v_writelane_b32 v255, s70, 62
	v_writelane_b32 v255, s71, 63
	v_writelane_b32 v254, s76, 0
	v_writelane_b32 v254, s77, 1
	v_writelane_b32 v254, s80, 2
	v_writelane_b32 v254, s81, 3
	v_writelane_b32 v254, s82, 4
	v_writelane_b32 v254, s83, 5
	v_writelane_b32 v254, s84, 6
	v_writelane_b32 v254, s85, 7
	v_writelane_b32 v254, s86, 8
	v_writelane_b32 v254, s87, 9
	v_writelane_b32 v254, s88, 10
	v_writelane_b32 v254, s89, 11
	v_writelane_b32 v254, s90, 12
	v_writelane_b32 v254, s91, 13
	v_writelane_b32 v254, s92, 14
	v_writelane_b32 v254, s93, 15
	v_writelane_b32 v254, s94, 16
	v_writelane_b32 v254, s95, 17
	v_writelane_b32 v254, s96, 18
	v_writelane_b32 v254, s97, 19
	s_sub_i32 s98, s24, 64
	s_lshl_b32 s98, s98, 3
	s_add_i32 s98, s98, s25
	s_add_i32 s98, s98, 0x9540
	s_movk_i32 s99, 0x600
	s_mov_b32 s100, 0xa418
	s_mov_b32 s101, 8
	s_add_u32 s0, s78, 0xfffffef0
	s_addc_u32 s1, s79, -1
	s_load_dwordx8 s[36:43], s[0:1], 0x40
	s_waitcnt lgkmcnt(0)
	s_branch .Lmy_h1_fwd

.LBB0_1571:
	s_cmpk_lg_i32 s33, 0x100
	s_cbranch_scc1 .Lmy_skip_p11
	s_cmp_lt_u32 s76, 108
	s_cbranch_scc1 .Lmy_skip_p11
	s_waitcnt vmcnt(0) lgkmcnt(0)
	s_barrier
	v_writelane_b32 v255, s0, 0
	v_writelane_b32 v255, s1, 1
	v_writelane_b32 v255, s2, 2
	v_writelane_b32 v255, s3, 3
	v_writelane_b32 v255, s4, 4
	v_writelane_b32 v255, s5, 5
	v_writelane_b32 v255, s6, 6
	v_writelane_b32 v255, s7, 7
	v_writelane_b32 v255, s8, 8
	v_writelane_b32 v255, s9, 9
	v_writelane_b32 v255, s10, 10
	v_writelane_b32 v255, s11, 11
	v_writelane_b32 v255, s12, 12
	v_writelane_b32 v255, s13, 13
	v_writelane_b32 v255, s14, 14
	v_writelane_b32 v255, s15, 15
	v_writelane_b32 v255, s16, 16
	v_writelane_b32 v255, s17, 17
	v_writelane_b32 v255, s18, 18
	v_writelane_b32 v255, s19, 19
	v_writelane_b32 v255, s20, 20
	v_writelane_b32 v255, s21, 21
	v_writelane_b32 v255, s22, 22
	v_writelane_b32 v255, s23, 23
	v_writelane_b32 v255, s26, 24
	v_writelane_b32 v255, s27, 25
	v_writelane_b32 v255, s34, 26
	v_writelane_b32 v255, s35, 27
	v_writelane_b32 v255, s36, 28
	v_writelane_b32 v255, s37, 29
	v_writelane_b32 v255, s38, 30
	v_writelane_b32 v255, s39, 31
	v_writelane_b32 v255, s40, 32
	v_writelane_b32 v255, s41, 33
	v_writelane_b32 v255, s42, 34
	v_writelane_b32 v255, s43, 35
	v_writelane_b32 v255, s44, 36
	v_writelane_b32 v255, s45, 37
	v_writelane_b32 v255, s46, 38
	v_writelane_b32 v255, s47, 39
	v_writelane_b32 v255, s48, 40
	v_writelane_b32 v255, s49, 41
	v_writelane_b32 v255, s50, 42
	v_writelane_b32 v255, s51, 43
	v_writelane_b32 v255, s52, 44
	v_writelane_b32 v255, s53, 45
	v_writelane_b32 v255, s54, 46
	v_writelane_b32 v255, s55, 47
	v_writelane_b32 v255, s56, 48
	v_writelane_b32 v255, s57, 49
	v_writelane_b32 v255, s58, 50
	v_writelane_b32 v255, s59, 51
	v_writelane_b32 v255, s60, 52
	v_writelane_b32 v255, s61, 53
	v_writelane_b32 v255, s62, 54
	v_writelane_b32 v255, s63, 55
	v_writelane_b32 v255, s64, 56
	v_writelane_b32 v255, s65, 57
	v_writelane_b32 v255, s66, 58
	v_writelane_b32 v255, s67, 59
	v_writelane_b32 v255, s68, 60
	v_writelane_b32 v255, s69, 61
	v_writelane_b32 v255, s70, 62
	v_writelane_b32 v255, s71, 63
	v_writelane_b32 v254, s76, 0
	v_writelane_b32 v254, s77, 1
	v_writelane_b32 v254, s80, 2
	v_writelane_b32 v254, s81, 3
	v_writelane_b32 v254, s82, 4
	v_writelane_b32 v254, s83, 5
	v_writelane_b32 v254, s84, 6
	v_writelane_b32 v254, s85, 7
	v_writelane_b32 v254, s86, 8
	v_writelane_b32 v254, s87, 9
	v_writelane_b32 v254, s88, 10
	v_writelane_b32 v254, s89, 11
	v_writelane_b32 v254, s90, 12
	v_writelane_b32 v254, s91, 13
	v_writelane_b32 v254, s92, 14
	v_writelane_b32 v254, s93, 15
	v_writelane_b32 v254, s94, 16
	v_writelane_b32 v254, s95, 17
	v_writelane_b32 v254, s96, 18
	v_writelane_b32 v254, s97, 19
	s_sub_i32 s98, s76, 108
	s_lshl_b32 s98, s98, 3
	s_add_i32 s98, s98, s25
	s_add_i32 s98, s98, 0xa418
	s_movk_i32 s99, 0x4a0
	s_mov_b32 s100, 0xcd00
	s_mov_b32 s101, 3
	s_add_u32 s0, s78, 0xfffffef0
	s_addc_u32 s1, s79, -1
	s_load_dwordx8 s[36:43], s[0:1], 0x40
	s_waitcnt lgkmcnt(0)
	s_branch .Lmy_h1_fwd

.LBB0_1891:
	s_cmpk_lg_i32 s33, 0x100
	s_cbranch_scc1 .Lmy_skip_p14
	s_cmp_lt_u32 s76, 108
	s_cbranch_scc1 .Lmy_skip_p14
	s_waitcnt vmcnt(0) lgkmcnt(0)
	s_barrier
	v_writelane_b32 v255, s0, 0
	v_writelane_b32 v255, s1, 1
	v_writelane_b32 v255, s2, 2
	v_writelane_b32 v255, s3, 3
	v_writelane_b32 v255, s4, 4
	v_writelane_b32 v255, s5, 5
	v_writelane_b32 v255, s6, 6
	v_writelane_b32 v255, s7, 7
	v_writelane_b32 v255, s8, 8
	v_writelane_b32 v255, s9, 9
	v_writelane_b32 v255, s10, 10
	v_writelane_b32 v255, s11, 11
	v_writelane_b32 v255, s12, 12
	v_writelane_b32 v255, s13, 13
	v_writelane_b32 v255, s14, 14
	v_writelane_b32 v255, s15, 15
	v_writelane_b32 v255, s16, 16
	v_writelane_b32 v255, s17, 17
	v_writelane_b32 v255, s18, 18
	v_writelane_b32 v255, s19, 19
	v_writelane_b32 v255, s20, 20
	v_writelane_b32 v255, s21, 21
	v_writelane_b32 v255, s22, 22
	v_writelane_b32 v255, s23, 23
	v_writelane_b32 v255, s26, 24
	v_writelane_b32 v255, s27, 25
	v_writelane_b32 v255, s34, 26
	v_writelane_b32 v255, s35, 27
	v_writelane_b32 v255, s36, 28
	v_writelane_b32 v255, s37, 29
	v_writelane_b32 v255, s38, 30
	v_writelane_b32 v255, s39, 31
	v_writelane_b32 v255, s40, 32
	v_writelane_b32 v255, s41, 33
	v_writelane_b32 v255, s42, 34
	v_writelane_b32 v255, s43, 35
	v_writelane_b32 v255, s44, 36
	v_writelane_b32 v255, s45, 37
	v_writelane_b32 v255, s46, 38
	v_writelane_b32 v255, s47, 39
	v_writelane_b32 v255, s48, 40
	v_writelane_b32 v255, s49, 41
	v_writelane_b32 v255, s50, 42
	v_writelane_b32 v255, s51, 43
	v_writelane_b32 v255, s52, 44
	v_writelane_b32 v255, s53, 45
	v_writelane_b32 v255, s54, 46
	v_writelane_b32 v255, s55, 47
	v_writelane_b32 v255, s56, 48
	v_writelane_b32 v255, s57, 49
	v_writelane_b32 v255, s58, 50
	v_writelane_b32 v255, s59, 51
	v_writelane_b32 v255, s60, 52
	v_writelane_b32 v255, s61, 53
	v_writelane_b32 v255, s62, 54
	v_writelane_b32 v255, s63, 55
	v_writelane_b32 v255, s64, 56
	v_writelane_b32 v255, s65, 57
	v_writelane_b32 v255, s66, 58
	v_writelane_b32 v255, s67, 59
	v_writelane_b32 v255, s68, 60
	v_writelane_b32 v255, s69, 61
	v_writelane_b32 v255, s70, 62
	v_writelane_b32 v255, s71, 63
	v_writelane_b32 v254, s76, 0
	v_writelane_b32 v254, s77, 1
	v_writelane_b32 v254, s80, 2
	v_writelane_b32 v254, s81, 3
	v_writelane_b32 v254, s82, 4
	v_writelane_b32 v254, s83, 5
	v_writelane_b32 v254, s84, 6
	v_writelane_b32 v254, s85, 7
	v_writelane_b32 v254, s86, 8
	v_writelane_b32 v254, s87, 9
	v_writelane_b32 v254, s88, 10
	v_writelane_b32 v254, s89, 11
	v_writelane_b32 v254, s90, 12
	v_writelane_b32 v254, s91, 13
	v_writelane_b32 v254, s92, 14
	v_writelane_b32 v254, s93, 15
	v_writelane_b32 v254, s94, 16
	v_writelane_b32 v254, s95, 17
	v_writelane_b32 v254, s96, 18
	v_writelane_b32 v254, s97, 19
	s_sub_i32 s98, s76, 108
	s_lshl_b32 s98, s98, 3
	s_add_i32 s98, s98, s25
	s_add_i32 s98, s98, 0xcd00
	s_movk_i32 s99, 0x4a0
	s_mov_b32 s100, 0xf200
	s_mov_b32 s101, 4
	s_add_u32 s0, s78, 0xfffffef0
	s_addc_u32 s1, s79, -1
	s_load_dwordx8 s[36:43], s[0:1], 0x40
	s_waitcnt lgkmcnt(0)
	s_branch .Lmy_h2_fwd

.LBB0_2241:
	s_waitcnt vmcnt(0)
	s_barrier
	s_cmpk_lg_i32 s33, 0x100
	s_cbranch_scc1 .Lmy_skip_p17
	s_cmp_lt_u32 s76, 48
	s_cbranch_scc1 .Lmy_skip_p17
	s_waitcnt vmcnt(0) lgkmcnt(0)
	s_barrier
	v_writelane_b32 v255, s0, 0
	v_writelane_b32 v255, s1, 1
	v_writelane_b32 v255, s2, 2
	v_writelane_b32 v255, s3, 3
	v_writelane_b32 v255, s4, 4
	v_writelane_b32 v255, s5, 5
	v_writelane_b32 v255, s6, 6
	v_writelane_b32 v255, s7, 7
	v_writelane_b32 v255, s8, 8
	v_writelane_b32 v255, s9, 9
	v_writelane_b32 v255, s10, 10
	v_writelane_b32 v255, s11, 11
	v_writelane_b32 v255, s12, 12
	v_writelane_b32 v255, s13, 13
	v_writelane_b32 v255, s14, 14
	v_writelane_b32 v255, s15, 15
	v_writelane_b32 v255, s16, 16
	v_writelane_b32 v255, s17, 17
	v_writelane_b32 v255, s18, 18
	v_writelane_b32 v255, s19, 19
	v_writelane_b32 v255, s20, 20
	v_writelane_b32 v255, s21, 21
	v_writelane_b32 v255, s22, 22
	v_writelane_b32 v255, s23, 23
	v_writelane_b32 v255, s26, 24
	v_writelane_b32 v255, s27, 25
	v_writelane_b32 v255, s34, 26
	v_writelane_b32 v255, s35, 27
	v_writelane_b32 v255, s36, 28
	v_writelane_b32 v255, s37, 29
	v_writelane_b32 v255, s38, 30
	v_writelane_b32 v255, s39, 31
	v_writelane_b32 v255, s40, 32
	v_writelane_b32 v255, s41, 33
	v_writelane_b32 v255, s42, 34
	v_writelane_b32 v255, s43, 35
	v_writelane_b32 v255, s44, 36
	v_writelane_b32 v255, s45, 37
	v_writelane_b32 v255, s46, 38
	v_writelane_b32 v255, s47, 39
	v_writelane_b32 v255, s48, 40
	v_writelane_b32 v255, s49, 41
	v_writelane_b32 v255, s50, 42
	v_writelane_b32 v255, s51, 43
	v_writelane_b32 v255, s52, 44
	v_writelane_b32 v255, s53, 45
	v_writelane_b32 v255, s54, 46
	v_writelane_b32 v255, s55, 47
	v_writelane_b32 v255, s56, 48
	v_writelane_b32 v255, s57, 49
	v_writelane_b32 v255, s58, 50
	v_writelane_b32 v255, s59, 51
	v_writelane_b32 v255, s60, 52
	v_writelane_b32 v255, s61, 53
	v_writelane_b32 v255, s62, 54
	v_writelane_b32 v255, s63, 55
	v_writelane_b32 v255, s64, 56
	v_writelane_b32 v255, s65, 57
	v_writelane_b32 v255, s66, 58
	v_writelane_b32 v255, s67, 59
	v_writelane_b32 v255, s68, 60
	v_writelane_b32 v255, s69, 61
	v_writelane_b32 v255, s70, 62
	v_writelane_b32 v255, s71, 63
	v_writelane_b32 v254, s76, 0
	v_writelane_b32 v254, s77, 1
	v_writelane_b32 v254, s80, 2
	v_writelane_b32 v254, s81, 3
	v_writelane_b32 v254, s82, 4
	v_writelane_b32 v254, s83, 5
	v_writelane_b32 v254, s84, 6
	v_writelane_b32 v254, s85, 7
	v_writelane_b32 v254, s86, 8
	v_writelane_b32 v254, s87, 9
	v_writelane_b32 v254, s88, 10
	v_writelane_b32 v254, s89, 11
	v_writelane_b32 v254, s90, 12
	v_writelane_b32 v254, s91, 13
	v_writelane_b32 v254, s92, 14
	v_writelane_b32 v254, s93, 15
	v_writelane_b32 v254, s94, 16
	v_writelane_b32 v254, s95, 17
	v_writelane_b32 v254, s96, 18
	v_writelane_b32 v254, s97, 19
	s_sub_i32 s98, s76, 48
	s_lshl_b32 s98, s98, 3
	s_add_i32 s98, s98, s25
	s_add_i32 s98, s98, 0xf200
	s_movk_i32 s99, 0x680
	s_mov_b32 s100, 0x12500
	s_mov_b32 s101, 5
	s_add_u32 s0, s78, 0xfffffef0
	s_addc_u32 s1, s79, -1
	s_load_dwordx8 s[36:43], s[0:1], 0x40
	s_waitcnt lgkmcnt(0)
	s_branch .Lmy_h2_fwd

.LBB0_2319:
	s_cmpk_lg_i32 s33, 0x100
	s_cbranch_scc1 .Lmy_skip_l18
	s_cmp_lt_u32 s24, 64
	s_cbranch_scc1 .Lmy_skip_l18
	s_waitcnt vmcnt(0) lgkmcnt(0)
	s_barrier
	v_writelane_b32 v255, s0, 0
	v_writelane_b32 v255, s1, 1
	v_writelane_b32 v255, s2, 2
	v_writelane_b32 v255, s3, 3
	v_writelane_b32 v255, s4, 4
	v_writelane_b32 v255, s5, 5
	v_writelane_b32 v255, s6, 6
	v_writelane_b32 v255, s7, 7
	v_writelane_b32 v255, s8, 8
	v_writelane_b32 v255, s9, 9
	v_writelane_b32 v255, s10, 10
	v_writelane_b32 v255, s11, 11
	v_writelane_b32 v255, s12, 12
	v_writelane_b32 v255, s13, 13
	v_writelane_b32 v255, s14, 14
	v_writelane_b32 v255, s15, 15
	v_writelane_b32 v255, s16, 16
	v_writelane_b32 v255, s17, 17
	v_writelane_b32 v255, s18, 18
	v_writelane_b32 v255, s19, 19
	v_writelane_b32 v255, s20, 20
	v_writelane_b32 v255, s21, 21
	v_writelane_b32 v255, s22, 22
	v_writelane_b32 v255, s23, 23
	v_writelane_b32 v255, s26, 24
	v_writelane_b32 v255, s27, 25
	v_writelane_b32 v255, s34, 26
	v_writelane_b32 v255, s35, 27
	v_writelane_b32 v255, s36, 28
	v_writelane_b32 v255, s37, 29
	v_writelane_b32 v255, s38, 30
	v_writelane_b32 v255, s39, 31
	v_writelane_b32 v255, s40, 32
	v_writelane_b32 v255, s41, 33
	v_writelane_b32 v255, s42, 34
	v_writelane_b32 v255, s43, 35
	v_writelane_b32 v255, s44, 36
	v_writelane_b32 v255, s45, 37
	v_writelane_b32 v255, s46, 38
	v_writelane_b32 v255, s47, 39
	v_writelane_b32 v255, s48, 40
	v_writelane_b32 v255, s49, 41
	v_writelane_b32 v255, s50, 42
	v_writelane_b32 v255, s51, 43
	v_writelane_b32 v255, s52, 44
	v_writelane_b32 v255, s53, 45
	v_writelane_b32 v255, s54, 46
	v_writelane_b32 v255, s55, 47
	v_writelane_b32 v255, s56, 48
	v_writelane_b32 v255, s57, 49
	v_writelane_b32 v255, s58, 50
	v_writelane_b32 v255, s59, 51
	v_writelane_b32 v255, s60, 52
	v_writelane_b32 v255, s61, 53
	v_writelane_b32 v255, s62, 54
	v_writelane_b32 v255, s63, 55
	v_writelane_b32 v255, s64, 56
	v_writelane_b32 v255, s65, 57
	v_writelane_b32 v255, s66, 58
	v_writelane_b32 v255, s67, 59
	v_writelane_b32 v255, s68, 60
	v_writelane_b32 v255, s69, 61
	v_writelane_b32 v255, s70, 62
	v_writelane_b32 v255, s71, 63
	v_writelane_b32 v254, s76, 0
	v_writelane_b32 v254, s77, 1
	v_writelane_b32 v254, s80, 2
	v_writelane_b32 v254, s81, 3
	v_writelane_b32 v254, s82, 4
	v_writelane_b32 v254, s83, 5
	v_writelane_b32 v254, s84, 6
	v_writelane_b32 v254, s85, 7
	v_writelane_b32 v254, s86, 8
	v_writelane_b32 v254, s87, 9
	v_writelane_b32 v254, s88, 10
	v_writelane_b32 v254, s89, 11
	v_writelane_b32 v254, s90, 12
	v_writelane_b32 v254, s91, 13
	v_writelane_b32 v254, s92, 14
	v_writelane_b32 v254, s93, 15
	v_writelane_b32 v254, s94, 16
	v_writelane_b32 v254, s95, 17
	v_writelane_b32 v254, s96, 18
	v_writelane_b32 v254, s97, 19
	s_sub_i32 s98, s24, 64
	s_lshl_b32 s98, s98, 3
	s_add_i32 s98, s98, s25
	s_add_i32 s98, s98, 0x12500
	s_movk_i32 s99, 0x600
	s_mov_b32 s100, 0x13a80
	s_mov_b32 s101, 10
	s_add_u32 s0, s78, 0xfffffef0
	s_addc_u32 s1, s79, -1
	s_load_dwordx8 s[36:43], s[0:1], 0x40
	s_waitcnt lgkmcnt(0)
	s_branch .Lmy_h2_fwd
